# WKV1 raw-row loads marked non-temporal (keep chunk records cache-resident for WKV2)
# baseline (speedup 1.0000x reference)
; __device__ __forceinline__ void ph_wkv1(const Params& p, int jl, LAS unsigned char* lds, int lane_in, int wave) {
;     ...
;     if (gw < BATCH * WH * WC_NCH) { int l0 = lane_in; asm volatile("" : "+v"(l0)); W1_LOAD_RAW(gw, l0); }
.LBB0_192:
	s_and_b64 vcc, exec, s[0:1]
	s_cbranch_vccz .LBB0_218
	s_load_dword s0, s[88:89], 0x0
	v_readlane_b32 s1, v255, 15
	s_waitcnt lgkmcnt(0)
	s_mul_i32 s1, s0, s1
	s_add_i32 s20, s1, s92
	s_cmpk_gt_i32 s20, 0x407f
	s_cbranch_scc1 .LBB0_218
	s_cmp_gt_u32 s68, 1
	s_cselect_b64 s[2:3], -1, 0
	s_cmp_lt_u32 s68, 2
	s_cselect_b64 s[4:5], -1, 0
	s_and_b64 vcc, s[4:5], exec
	s_mov_b32 s1, 0x1d100000
	s_cselect_b32 s1, 0x10e00000, s1
	s_add_u32 s6, s66, s1
	s_mul_hi_i32 s1, s20, 0xfe03f81
	s_addc_u32 s7, s67, 0
	s_lshr_b32 s4, s1, 31
	s_ashr_i32 s1, s1, 3
	s_add_i32 s1, s1, s4
	s_mul_i32 s4, s1, 0x81
	s_sub_i32 s4, s20, s4
	s_lshr_b32 s5, s1, 4
	v_mov_b32_e32 v0, v238
	s_mulk_i32 s5, 0x810
	s_lshl_b32 s4, s4, 4
	s_lshl_b32 s1, s1, 6
	s_add_i32 s5, s5, s4
	s_and_b32 s1, s1, 0x3c0
	v_and_or_b32 v4, v0, 15, s5
	v_and_or_b32 v2, v0, 16, s1
	v_ashrrev_i32_e32 v0, 2, v0
	v_and_b32_e32 v0, -8, v0
	v_add_u32_e32 v6, v2, v0
	v_ashrrev_i32_e32 v5, 31, v4
	v_lshlrev_b64 v[2:3], 10, v[4:5]
	v_ashrrev_i32_e32 v7, 31, v6
	v_lshl_add_u64 v[2:3], v[2:3], 0, v[6:7]
	v_readlane_b32 s4, v252, 40
	v_lshlrev_b64 v[8:9], 1, v[2:3]
	v_readlane_b32 s5, v252, 41
	v_lshlrev_b64 v[4:5], 13, v[4:5]
	s_waitcnt vmcnt(0)
	v_lshl_add_u64 v[40:41], s[6:7], 0, v[8:9]
	v_lshl_add_u64 v[10:11], s[4:5], 0, v[8:9]
	v_readlane_b32 s4, v252, 32
	v_readlane_b32 s5, v252, 33
	s_nop 1
	v_lshl_add_u64 v[4:5], s[4:5], 0, v[4:5]
	v_readlane_b32 s4, v252, 30
	v_readlane_b32 s5, v252, 31
	v_lshl_add_u64 v[44:45], v[6:7], 1, v[4:5]
	s_waitcnt vmcnt(2)
	v_lshl_add_u64 v[32:33], s[4:5], 0, v[8:9]
	global_load_dwordx4 v[4:7], v[10:11], off nt
	s_nop 0
	global_load_dwordx4 v[8:11], v[10:11], off offset:64 nt
	s_nop 0
	global_load_dwordx4 v[12:15], v[44:45], off nt
	global_load_dwordx4 v[16:19], v[44:45], off offset:64 nt
	global_load_dwordx4 v[20:23], v[44:45], off offset:2048 nt
	global_load_dwordx4 v[24:27], v[44:45], off offset:2112 nt
	global_load_dwordx4 v[28:31], v[32:33], off nt
	s_nop 0
	global_load_dwordx4 v[32:35], v[32:33], off offset:64 nt
	s_nop 0
	global_load_dwordx4 v[36:39], v[40:41], off nt
	s_nop 0
	global_load_dwordx4 v[40:43], v[40:41], off offset:64 nt
	s_cbranch_vccnz .LBB0_196
	v_readlane_b32 s4, v252, 42
	v_readlane_b32 s5, v252, 43
	v_add_co_u32_e32 v56, vcc, 0x1000, v44
	s_nop 0
	v_lshl_add_u64 v[2:3], v[2:3], 1, s[4:5]
	v_addc_co_u32_e32 v57, vcc, 0, v45, vcc
	global_load_dwordx4 v[44:47], v[2:3], off nt
	global_load_dwordx4 v[48:51], v[2:3], off offset:64 nt
	global_load_dwordx4 v[52:55], v[56:57], off offset:2048 nt
	s_nop 0
	global_load_dwordx4 v[56:59], v[56:57], off offset:2112 nt
	s_branch .LBB0_197

; #define LAS __attribute__((address_space(3)))
; __device__ __forceinline__ v2u pk4(const f32x4 v) { return __builtin_bit_cast(v2u, __builtin_convertvector(v, bf4v)); }
; __device__ __forceinline__ float sigmoidf_(float x) { return rcpf_(1.f + __expf(-x)); }
; __device__ __forceinline__ float psum16(float x) { x += dppz<0x111>(x); x += dppz<0x112>(x); x += dppz<0x114>(x); x += dppz<0x118>(x); return x; }
; __device__ __forceinline__ void ph_wkv1(const Params& p, int jl, LAS unsigned char* lds, int lane_in, int wave) {
;     ...
;             for (int e = 0; e < 4; ++e) {
;                 const float a = sigmoidf_(pa0[e] + la2[e]), d = CL2 * sigmoidf_(pw0[e] + lw2[e]), cum = psum16(d);
;                 const float g = __builtin_amdgcn_exp2f(-cum), ig = __builtin_amdgcn_exp2f(cum), gp = __builtin_amdgcn_exp2f(d - cum), nk = -kk[jt][e] * inv;
;                 kt[e] = kraw[jt][e] * (1.f + (a - 1.f) * pka[e]);
;                 bonp = fmaf(rr[e] * kt[e], prk[e], bonp);
;                 at[e] = nk * gp; bt[e] = -nk * a * ig; kq[e] = kt[e] * ig; rq[e] = rr[e] * g; gg[e] = g;
;             }
;             pa[jt] = pk4(at); pb[jt] = pk4(bt); pk[jt] = pk4(kq); pr[jt] = pk4(rq); rt[jt] = rq; pvp[jt] = pk4(vp); ggv[jt] = gg;
;             *(LAS v2u*)(iw + 0 * IMG + 32 * jt) = pa[jt]; *(LAS v2u*)(iw + 1 * IMG + 32 * jt) = pb[jt]; *(LAS v2u*)(iw + 2 * IMG + 32 * jt) = pk[jt]; *(LAS v2u*)(iw + 3 * IMG + 32 * jt) = pvp[jt];
;         }
;     ...
;         if (job + NGW < BATCH * WH * WC_NCH) W1_LOAD_RAW(job + NGW, lane);
.LBB0_207:
	v_lshlrev_b32_e32 v106, 16, v178
	v_and_b32_e32 v107, 0xffff0000, v178
	v_lshlrev_b32_e32 v110, 16, v180
	v_and_b32_e32 v111, 0xffff0000, v180
	v_add_f32_e32 v96, v96, v106
	v_add_f32_e32 v92, v92, v110
	v_add_f32_e32 v97, v97, v107
	v_add_f32_e32 v93, v93, v111
	v_mul_f32_e32 v96, 0xbfb8aa3b, v96
	v_mul_f32_e32 v92, 0xbfb8aa3b, v92
	v_mul_f32_e32 v97, 0xbfb8aa3b, v97
	v_mul_f32_e32 v93, 0xbfb8aa3b, v93
	v_exp_f32_e32 v96, v96
	v_exp_f32_e32 v92, v92
	v_exp_f32_e32 v97, v97
	v_exp_f32_e32 v93, v93
	v_lshlrev_b32_e32 v142, 16, v179
	v_add_f32_e32 v98, v98, v142
	v_add_f32_e32 v96, 1.0, v96
	v_add_f32_e32 v92, 1.0, v92
	v_add_f32_e32 v97, 1.0, v97
	v_add_f32_e32 v93, 1.0, v93
	v_mul_f32_e32 v98, 0xbfb8aa3b, v98
	v_rcp_f32_e32 v110, v96
	v_rcp_f32_e32 v96, v92
	v_rcp_f32_e32 v111, v97
	v_rcp_f32_e32 v97, v93
	v_exp_f32_e32 v98, v98
	v_and_b32_e32 v143, 0xffff0000, v179
	v_xor_b32_e32 v115, 0x80000000, v137
	v_xor_b32_e32 v114, 0x80000000, v136
	v_pk_add_f32 v[136:137], v[96:97], -1.0 op_sel_hi:[1,0]
	v_add_f32_e32 v98, 1.0, v98
	s_waitcnt vmcnt(2)
	v_pk_fma_f32 v[88:89], v[88:89], v[136:137], 1.0 op_sel_hi:[1,1,0]
	v_rcp_f32_e32 v136, v98
	v_add_f32_e32 v99, v99, v143
	v_mul_f32_e32 v99, 0xbfb8aa3b, v99
	v_lshlrev_b32_e32 v146, 16, v0
	v_exp_f32_e32 v99, v99
	v_and_b32_e32 v0, 0xffff0000, v0
	v_add_f32_e32 v94, v94, v146
	v_mul_f32_e32 v94, 0xbfb8aa3b, v94
	v_pk_mul_f32 v[132:133], v[88:89], v[132:133]
	v_mul_f32_e32 v89, 0x3f60028a, v136
	v_add_f32_e32 v0, v95, v0
	v_exp_f32_e32 v94, v94
	v_mov_b32_dpp v89, v89 row_shr:1 row_mask:0xf bank_mask:0xf bound_ctrl:1
	v_mul_f32_e32 v0, 0xbfb8aa3b, v0
	v_fmac_f32_e32 v89, 0x3f60028a, v136
	v_exp_f32_e32 v0, v0
	v_add_f32_e32 v95, 1.0, v99
	v_add_f32_dpp v89, v89, v89 row_shr:2 row_mask:0xf bank_mask:0xf bound_ctrl:1
	v_rcp_f32_e32 v99, v95
	v_add_f32_e32 v88, 1.0, v94
	v_add_f32_dpp v89, v89, v89 row_shr:4 row_mask:0xf bank_mask:0xf bound_ctrl:1
	v_add_f32_e32 v0, 1.0, v0
	v_mul_f32_e32 v92, 0x3f60028a, v110
	v_add_f32_dpp v94, v89, v89 row_shr:8 row_mask:0xf bank_mask:0xf bound_ctrl:1
	v_fma_f32 v89, v136, s0, -v94
	v_exp_f32_e32 v136, v89
	v_rcp_f32_e32 v89, v0
	v_mul_f32_e32 v0, 0x3f60028a, v99
	v_mul_f32_e32 v93, 0x3f60028a, v111
	v_mov_b32_dpp v92, v92 row_shr:1 row_mask:0xf bank_mask:0xf bound_ctrl:1
	v_mov_b32_dpp v0, v0 row_shr:1 row_mask:0xf bank_mask:0xf bound_ctrl:1
	v_fmac_f32_e32 v0, 0x3f60028a, v99
	v_mov_b32_dpp v93, v93 row_shr:1 row_mask:0xf bank_mask:0xf bound_ctrl:1
	v_fmac_f32_e32 v92, 0x3f60028a, v110
	v_add_f32_dpp v0, v0, v0 row_shr:2 row_mask:0xf bank_mask:0xf bound_ctrl:1
	v_fmac_f32_e32 v93, 0x3f60028a, v111
	v_add_f32_dpp v92, v92, v92 row_shr:2 row_mask:0xf bank_mask:0xf bound_ctrl:1
	v_add_f32_dpp v0, v0, v0 row_shr:4 row_mask:0xf bank_mask:0xf bound_ctrl:1
	v_add_f32_dpp v93, v93, v93 row_shr:2 row_mask:0xf bank_mask:0xf bound_ctrl:1
	v_add_f32_dpp v92, v92, v92 row_shr:4 row_mask:0xf bank_mask:0xf bound_ctrl:1
	v_add_f32_dpp v95, v0, v0 row_shr:8 row_mask:0xf bank_mask:0xf bound_ctrl:1
	v_add_f32_dpp v93, v93, v93 row_shr:4 row_mask:0xf bank_mask:0xf bound_ctrl:1
	v_fma_f32 v0, v99, s0, -v95
	v_add_f32_dpp v92, v92, v92 row_shr:8 row_mask:0xf bank_mask:0xf bound_ctrl:1
	v_add_f32_dpp v93, v93, v93 row_shr:8 row_mask:0xf bank_mask:0xf bound_ctrl:1
	v_rcp_f32_e32 v88, v88
	v_exp_f32_e32 v137, v0
	v_fma_f32 v110, v110, s0, -v92
	v_fma_f32 v111, v111, s0, -v93
	v_exp_f32_e32 v110, v110
	v_exp_f32_e32 v111, v111
	v_exp_f32_e32 v106, v92
	v_exp_f32_e32 v107, v93
	v_exp_f32_e32 v98, v94
	v_exp_f32_e32 v99, v95
	v_pk_mul_f32 v[114:115], v[138:139], v[114:115]
	v_pk_mul_f32 v[134:135], v[138:139], v[134:135] neg_lo:[0,1] neg_hi:[0,1]
	v_pk_mul_f32 v[136:137], v[114:115], v[136:137]
	v_pk_mul_f32 v[114:115], v[88:89], v[114:115] neg_lo:[0,1] neg_hi:[0,1]
	v_pk_add_f32 v[88:89], v[88:89], -1.0 op_sel_hi:[1,0]
	s_add_i32 s22, s20, s12
	v_pk_fma_f32 v[88:89], v[90:91], v[88:89], 1.0 op_sel_hi:[1,1,0]
	v_pk_mul_f32 v[110:111], v[134:135], v[110:111]
	v_pk_mul_f32 v[96:97], v[96:97], v[134:135] neg_lo:[0,1] neg_hi:[0,1]
	v_pk_mul_f32 v[134:135], v[88:89], v[2:3]
	s_cmpk_gt_i32 s22, 0x407f
	v_pk_mul_f32 v[96:97], v[96:97], v[106:107]
	v_pk_mul_f32 v[138:139], v[114:115], v[98:99]
	v_pk_mul_f32 v[2:3], v[132:133], v[106:107]
	v_pk_mul_f32 v[88:89], v[134:135], v[98:99]
	s_cselect_b64 s[10:11], -1, 0
	v_cvt_pk_bf16_f32 v115, v136, v137
	v_cvt_pk_bf16_f32 v114, v110, v111
	v_cvt_pk_bf16_f32 v111, v138, v139
	v_cvt_pk_bf16_f32 v110, v96, v97
	v_cvt_pk_bf16_f32 v107, v88, v89
	v_cvt_pk_bf16_f32 v106, v2, v3
	v_cvt_pk_bf16_f32 v119, v118, v119
	v_cvt_pk_bf16_f32 v118, v140, v141
	s_mov_b64 s[0:1], -1
	s_and_b64 vcc, exec, s[10:11]
	ds_write_b64 v187, v[114:115] offset:96
	ds_write_b64 v187, v[110:111] offset:2400
	ds_write_b64 v187, v[106:107] offset:4704
	ds_write_b64 v187, v[118:119] offset:7008
	s_cbranch_vccnz .LBB0_211
	s_mul_hi_i32 s0, s22, 0xfe03f81
	s_lshr_b32 s1, s0, 31
	s_ashr_i32 s0, s0, 3
	s_add_i32 s0, s0, s1
	s_lshr_b32 s1, s0, 4
	s_mulk_i32 s1, 0x810
	v_or_b32_e32 v0, s1, v166
	s_mul_i32 s1, s0, 0x810
	v_subrev_u32_e32 v0, s1, v0
	s_add_i32 s1, s19, s18
	s_lshl_b32 s0, s0, 6
	v_ashrrev_i32_e32 v2, 2, v164
	v_add_u32_e32 v4, s1, v0
	s_and_b32 s0, s0, 0x3c0
	v_and_b32_e32 v0, 16, v164
	v_and_b32_e32 v2, -8, v2
	v_add3_u32 v6, v2, v0, s0
	v_ashrrev_i32_e32 v5, 31, v4
	v_lshlrev_b64 v[2:3], 10, v[4:5]
	v_ashrrev_i32_e32 v7, 31, v6
	v_lshl_add_u64 v[2:3], v[2:3], 0, v[6:7]
	v_readlane_b32 s0, v252, 40
	v_lshlrev_b64 v[8:9], 1, v[2:3]
	v_readlane_b32 s1, v252, 41
	v_lshlrev_b64 v[4:5], 13, v[4:5]
	v_lshl_add_u64 v[40:41], s[6:7], 0, v[8:9]
	v_lshl_add_u64 v[10:11], s[0:1], 0, v[8:9]
	v_readlane_b32 s0, v252, 32
	v_readlane_b32 s1, v252, 33
	s_and_b64 vcc, exec, s[2:3]
	s_nop 0
	v_lshl_add_u64 v[4:5], s[0:1], 0, v[4:5]
	v_readlane_b32 s0, v252, 30
	v_readlane_b32 s1, v252, 31
	v_lshl_add_u64 v[44:45], v[6:7], 1, v[4:5]
	s_nop 0
	v_lshl_add_u64 v[32:33], s[0:1], 0, v[8:9]
	global_load_dwordx4 v[4:7], v[10:11], off nt
	s_nop 0
	global_load_dwordx4 v[8:11], v[10:11], off offset:64 nt
	s_nop 0
	global_load_dwordx4 v[12:15], v[44:45], off nt
	global_load_dwordx4 v[16:19], v[44:45], off offset:64 nt
	global_load_dwordx4 v[20:23], v[44:45], off offset:2048 nt
	global_load_dwordx4 v[24:27], v[44:45], off offset:2112 nt
	global_load_dwordx4 v[28:31], v[32:33], off nt
	s_nop 0
	global_load_dwordx4 v[32:35], v[32:33], off offset:64 nt
	s_nop 0
	global_load_dwordx4 v[36:39], v[40:41], off nt
	s_nop 0
	global_load_dwordx4 v[40:43], v[40:41], off offset:64 nt
	s_cbranch_vccz .LBB0_210
	v_readlane_b32 s0, v252, 42
	v_readlane_b32 s1, v252, 43
	v_add_co_u32_e32 v56, vcc, 0x1000, v44
	s_nop 0
	v_lshl_add_u64 v[2:3], v[2:3], 1, s[0:1]
	v_addc_co_u32_e32 v57, vcc, 0, v45, vcc
	global_load_dwordx4 v[44:47], v[2:3], off nt
	global_load_dwordx4 v[48:51], v[2:3], off offset:64 nt
	global_load_dwordx4 v[52:55], v[56:57], off offset:2048 nt
	s_nop 0
	global_load_dwordx4 v[56:59], v[56:57], off offset:2112 nt
	s_mov_b64 s[0:1], -1
	s_branch .LBB0_211
